# latent phase: one exposed load wait per step instead of two, wave sums via DPP + readlane
# baseline (speedup 1.0000x reference)
.LBB0_1141:
	s_or_b64 exec, exec, s[22:23]
	v_and_b32_e32 v39, 0xffff0000, v57
	v_and_b32_e32 v49, 0xffff0000, v55
	v_lshlrev_b32_e32 v38, 16, v57
	v_lshlrev_b32_e32 v40, 16, v56
	v_and_b32_e32 v41, 0xffff0000, v56
	v_lshlrev_b32_e32 v48, 16, v55
	v_mov_b32_e32 v60, v39
	v_mov_b32_e32 v61, v49
	v_pk_mul_f32 v[56:57], v[40:41], v[40:41]
	v_mov_b32_e32 v58, v38
	v_mov_b32_e32 v59, v48
	v_pk_mul_f32 v[60:61], v[60:61], v[60:61]
	v_add_f32_e32 v5, v56, v57
	v_pk_fma_f32 v[58:59], v[58:59], v[58:59], v[60:61]
	s_add_i32 s27, s27, 2
	v_add_f32_e32 v5, v58, v5
	v_add_f32_e32 v5, v5, v59
	v_mad_i64_i32 v[56:57], s[20:21], s20, v54, v[18:19]
	v_lshl_add_u64 v[22:23], v[22:23], 0, s[12:13]
	v_lshl_add_u64 v[24:25], v[24:25], 0, s[12:13]
	v_lshl_add_u64 v[26:27], v[26:27], 0, s[14:15]
	v_lshl_add_u64 v[28:29], v[28:29], 0, s[16:17]
	v_lshl_add_u64 v[30:31], v[30:31], 0, s[16:17]
	v_lshl_add_u64 v[32:33], v[32:33], 0, s[16:17]
	s_cmp_lt_i32 s27, s26
	v_lshl_add_u64 v[34:35], v[34:35], 0, s[18:19]
	s_nop 1
	v_add_f32_dpp v5, v5, v5 row_shr:1 row_mask:0xf bank_mask:0xf
	s_nop 1
	v_add_f32_dpp v5, v5, v5 row_shr:2 row_mask:0xf bank_mask:0xf
	s_nop 1
	v_add_f32_dpp v5, v5, v5 row_shr:4 row_mask:0xf bank_mask:0xf
	s_nop 1
	v_add_f32_dpp v5, v5, v5 row_shr:8 row_mask:0xf bank_mask:0xf
	s_nop 1
	v_add_f32_dpp v5, v5, v5 row_bcast:15 row_mask:0xa bank_mask:0xf
	s_nop 1
	v_add_f32_dpp v5, v5, v5 row_bcast:31 row_mask:0xc bank_mask:0xf
	s_nop 1
	v_readlane_b32 s34, v5, 63
	v_mov_b32_e32 v5, s34
	v_fmamk_f32 v5, v5, 0x3b2aaaab, v36
	v_mul_f32_e32 v7, 0x4b800000, v5
	v_cmp_gt_f32_e32 vcc, s31, v5
	s_nop 1
	v_cndmask_b32_e32 v5, v5, v7, vcc
	v_rsq_f32_e32 v5, v5
	s_nop 0
	v_mul_f32_e32 v7, 0x45800000, v5
	v_cndmask_b32_e32 v42, v5, v7, vcc
	v_pk_mul_f32 v[38:39], v[42:43], v[38:39] op_sel_hi:[0,1]
	v_pk_mul_f32 v[40:41], v[42:43], v[40:41] op_sel_hi:[0,1]
	v_pk_mul_f32 v[48:49], v[42:43], v[48:49] op_sel_hi:[0,1]
	v_pk_mul_f32 v[38:39], v[8:9], v[38:39]
	v_pk_mul_f32 v[40:41], v[10:11], v[40:41]
	v_pk_mul_f32 v[48:49], v[12:13], v[48:49]
	v_cvt_pk_bf16_f32 v5, v38, v39
	v_cvt_pk_bf16_f32 v7, v40, v41
	v_cvt_pk_bf16_f32 v37, v48, v49
	global_store_dword v[56:57], v5, off
	global_store_dword v[56:57], v7, off offset:256
	global_store_dword v[56:57], v37, off offset:512
	s_cbranch_scc0 .LBB0_1150
.LBB0_1142:
	v_lshl_add_u64 v[40:41], s[46:47], 0, v[32:33]
	v_lshl_add_u64 v[38:39], s[46:47], 0, v[30:31]
	v_add_co_u32_e32 v40, vcc, 0x12000000, v40
	v_mov_b32_e32 v44, 0
	s_nop 0
	v_addc_co_u32_e32 v41, vcc, 0, v41, vcc
	global_load_dwordx2 v[48:49], v[38:39], off
	global_load_dword v60, v[40:41], off
	global_load_dword v59, v[40:41], off offset:256
	global_load_dword v58, v[40:41], off offset:512
	v_mov_b32_e32 v38, 0
	v_mov_b32_e32 v42, 0
	v_mov_b32_e32 v46, 0
	v_mov_b32_e32 v72, 0
	v_mov_b32_e32 v73, 0
	s_and_saveexec_b64 s[20:21], s[0:1]
	s_cbranch_execz .LBB0_1144
	v_lshl_add_u64 v[38:39], s[46:47], 0, v[28:29]
	v_add_co_u32_e32 v38, vcc, 0x10000000, v38
	v_lshl_add_u64 v[40:41], s[46:47], 0, v[22:23]
	s_nop 0
	v_addc_co_u32_e32 v39, vcc, 0, v39, vcc
	v_add_co_u32_e32 v56, vcc, 0x200000, v40
	s_nop 1
	v_addc_co_u32_e32 v57, vcc, 0, v41, vcc
	v_add_co_u32_e32 v40, vcc, 0x600000, v40
	s_nop 1
	v_addc_co_u32_e32 v41, vcc, 0, v41, vcc
	global_load_ushort v72, v[38:39], off offset:512
	global_load_ushort v73, v[38:39], off offset:576
	global_load_dword v42, v[56:57], off
	s_nop 0
	global_load_dword v38, v[40:41], off

.LBB0_1146:
	s_or_b64 exec, exec, s[24:25]
	s_waitcnt vmcnt(0)
	v_lshlrev_b32_e32 v46, 16, v72
	v_lshlrev_b32_e32 v44, 16, v73
	v_lshlrev_b32_e32 v63, 16, v49
	v_lshlrev_b32_e32 v62, 16, v48
	v_and_b32_e32 v49, 0xffff0000, v49
	v_and_b32_e32 v48, 0xffff0000, v48
	v_pk_mul_f32 v[64:65], v[48:49], v[48:49]
	s_nop 0
	v_pk_fma_f32 v[64:65], v[62:63], v[62:63], v[64:65]
	s_nop 0
	v_add_f32_e32 v61, v64, v65
	v_mov_b32_e32 v65, v48
	v_mov_b32_e32 v48, v63
	s_nop 1
	v_add_f32_dpp v61, v61, v61 row_shr:1 row_mask:0xf bank_mask:0xf
	s_nop 1
	v_add_f32_dpp v61, v61, v61 row_shr:2 row_mask:0xf bank_mask:0xf
	s_nop 1
	v_add_f32_dpp v61, v61, v61 row_shr:4 row_mask:0xf bank_mask:0xf
	s_nop 1
	v_add_f32_dpp v61, v61, v61 row_shr:8 row_mask:0xf bank_mask:0xf
	s_nop 1
	v_add_f32_dpp v61, v61, v61 row_bcast:15 row_mask:0xa bank_mask:0xf
	s_nop 1
	v_add_f32_dpp v61, v61, v61 row_bcast:31 row_mask:0xc bank_mask:0xf
	s_nop 1
	v_readlane_b32 s34, v61, 63
	v_mov_b32_e32 v61, s34
	v_fmamk_f32 v61, v61, 0x3b800000, v36
	v_mul_f32_e32 v64, 0x4b800000, v61
	v_cmp_gt_f32_e32 vcc, s31, v61
	s_nop 1
	v_cndmask_b32_e32 v61, v61, v64, vcc
	v_rsq_f32_e32 v61, v61
	v_mov_b32_e32 v64, v62
	v_mul_f32_e32 v62, 0x45800000, v61
	v_cndmask_b32_e32 v62, v61, v62, vcc
	v_pk_mul_f32 v[64:65], v[62:63], v[64:65] op_sel_hi:[0,1]
	v_pk_mul_f32 v[48:49], v[62:63], v[48:49] op_sel_hi:[0,1]
	v_pk_mul_f32 v[48:49], v[2:3], v[48:49]
	v_pk_mul_f32 v[62:63], v[0:1], v[64:65]
	s_nop 0
	v_cvt_pk_bf16_f32 v62, v62, v63
	v_cvt_pk_bf16_f32 v63, v48, v49
	v_lshl_add_u64 v[48:49], s[46:47], 0, v[34:35]
	global_store_dwordx2 v[48:49], v[62:63], off
	s_and_saveexec_b64 s[22:23], s[0:1]
	s_cbranch_execz .LBB0_1148
	v_mul_f32_e32 v48, v42, v46
	v_fma_f32 v48, -v44, v38, v48
	v_cvt_pk_bf16_f32 v61, v48, s0
	v_lshl_add_u64 v[48:49], s[46:47], 0, v[24:25]
	v_mul_f32_e32 v42, v44, v42
	v_add_co_u32_e32 v48, vcc, 0x15000000, v48
	v_fmac_f32_e32 v42, v38, v46
	s_nop 0
	v_addc_co_u32_e32 v49, vcc, 0, v49, vcc
	v_cvt_pk_bf16_f32 v38, v42, s0
	global_store_short v[48:49], v61, off
	global_store_short v[48:49], v38, off offset:64
.LBB0_1148:
	s_or_b64 exec, exec, s[22:23]
	v_and_b32_e32 v49, 0xffff0000, v60
	v_and_b32_e32 v63, 0xffff0000, v58
	v_lshlrev_b32_e32 v48, 16, v60
	v_lshlrev_b32_e32 v62, 16, v58
	v_mov_b32_e32 v66, v49
	v_mov_b32_e32 v67, v63
	v_and_b32_e32 v61, 0xffff0000, v59
	v_mov_b32_e32 v64, v48
	v_mov_b32_e32 v65, v62
	v_pk_mul_f32 v[66:67], v[66:67], v[66:67]
	v_lshlrev_b32_e32 v60, 16, v59
	v_mul_f32_e32 v38, v61, v61
	v_pk_fma_f32 v[64:65], v[64:65], v[64:65], v[66:67]
	v_lshlrev_b32_e32 v67, 16, v41
	v_lshlrev_b32_e32 v66, 16, v40
	v_and_b32_e32 v41, 0xffff0000, v41
	v_and_b32_e32 v40, 0xffff0000, v40
	v_pk_fma_f32 v[58:59], v[60:61], v[60:61], v[38:39] op_sel_hi:[1,1,0]
	v_pk_mul_f32 v[68:69], v[40:41], v[40:41]
	v_pk_add_f32 v[58:59], v[64:65], v[58:59]
	v_pk_fma_f32 v[68:69], v[66:67], v[66:67], v[68:69]
	v_mov_b32_e32 v71, v58
	v_mov_b32_e32 v70, v68
	v_mov_b32_e32 v64, v69
	v_pk_add_f32 v[58:59], v[70:71], v[64:65]
	s_lshl_b64 s[22:23], s[20:21], 9
	s_nop 1
	v_add_f32_dpp v58, v58, v58 row_shr:1 row_mask:0xf bank_mask:0xf
	v_add_f32_dpp v59, v59, v59 row_shr:1 row_mask:0xf bank_mask:0xf
	s_nop 0
	v_add_f32_dpp v58, v58, v58 row_shr:2 row_mask:0xf bank_mask:0xf
	v_add_f32_dpp v59, v59, v59 row_shr:2 row_mask:0xf bank_mask:0xf
	s_nop 0
	v_add_f32_dpp v58, v58, v58 row_shr:4 row_mask:0xf bank_mask:0xf
	v_add_f32_dpp v59, v59, v59 row_shr:4 row_mask:0xf bank_mask:0xf
	s_nop 0
	v_add_f32_dpp v58, v58, v58 row_shr:8 row_mask:0xf bank_mask:0xf
	v_add_f32_dpp v59, v59, v59 row_shr:8 row_mask:0xf bank_mask:0xf
	s_nop 0
	v_add_f32_dpp v58, v58, v58 row_bcast:15 row_mask:0xa bank_mask:0xf
	v_add_f32_dpp v59, v59, v59 row_bcast:15 row_mask:0xa bank_mask:0xf
	s_nop 0
	v_add_f32_dpp v58, v58, v58 row_bcast:31 row_mask:0xc bank_mask:0xf
	v_add_f32_dpp v59, v59, v59 row_bcast:31 row_mask:0xc bank_mask:0xf
	s_nop 0
	s_nop 0
	v_readlane_b32 s34, v58, 63
	v_readlane_b32 s35, v59, 63
	v_mov_b32_e32 v58, s34
	v_mov_b32_e32 v59, s35
	s_nop 0
	v_pk_fma_f32 v[58:59], v[58:59], s[10:11], v[36:37] op_sel_hi:[1,1,0]
	v_lshl_add_u64 v[64:65], s[46:47], 0, v[26:27]
	v_mul_f32_e32 v38, 0x4b800000, v59
	v_cmp_gt_f32_e32 vcc, s31, v59
	s_nop 1
	v_cndmask_b32_e32 v38, v59, v38, vcc
	v_rsq_f32_e32 v38, v38
	s_nop 0
	v_mul_f32_e32 v42, 0x45800000, v38
	v_cndmask_b32_e32 v38, v38, v42, vcc
	v_pk_mul_f32 v[48:49], v[38:39], v[48:49] op_sel_hi:[0,1]
	v_pk_mul_f32 v[48:49], v[8:9], v[48:49]
	v_pk_mul_f32 v[60:61], v[38:39], v[60:61] op_sel_hi:[0,1]
	v_cvt_pk_bf16_f32 v42, v48, v49
	v_add_co_u32_e32 v48, vcc, s33, v64
	v_pk_mul_f32 v[60:61], v[10:11], v[60:61]
	s_nop 0
	v_addc_co_u32_e32 v49, vcc, 0, v65, vcc
	global_store_dword v[48:49], v42, off
	v_cvt_pk_bf16_f32 v42, v60, v61
	v_pk_mul_f32 v[60:61], v[38:39], v[62:63] op_sel_hi:[0,1]
	v_mul_f32_e32 v38, 0x4b800000, v58
	v_cmp_gt_f32_e32 vcc, s31, v58
	global_store_dword v[48:49], v42, off offset:256
	s_nop 0
	v_cndmask_b32_e32 v38, v58, v38, vcc
	v_rsq_f32_e32 v38, v38
	v_pk_mul_f32 v[58:59], v[12:13], v[60:61]
	s_nop 0
	v_cvt_pk_bf16_f32 v42, v58, v59
	global_store_dword v[48:49], v42, off offset:512
	v_mul_f32_e32 v42, 0x45800000, v38
	v_cndmask_b32_e32 v38, v38, v42, vcc
	v_mov_b32_e32 v48, v66
	v_mov_b32_e32 v49, v40
	v_mov_b32_e32 v40, v67
	v_pk_mul_f32 v[48:49], v[38:39], v[48:49] op_sel_hi:[0,1]
	v_pk_mul_f32 v[40:41], v[38:39], v[40:41] op_sel_hi:[0,1]
	v_pk_mul_f32 v[40:41], v[2:3], v[40:41]
	v_pk_mul_f32 v[48:49], v[0:1], v[48:49]
	s_nop 0
	v_cvt_pk_bf16_f32 v48, v48, v49
	v_cvt_pk_bf16_f32 v49, v40, v41
	v_lshl_add_u64 v[40:41], v[16:17], 0, s[22:23]
	global_store_dwordx2 v[40:41], v[48:49], off
	s_and_saveexec_b64 s[22:23], s[0:1]
	s_cbranch_execz .LBB0_1141
	v_mul_f32_e32 v38, v7, v5
	v_fma_f32 v38, -v39, v37, v38
	v_mul_f32_e32 v7, v39, v7
	s_lshl_b64 s[24:25], s[20:21], 7
	v_cvt_pk_bf16_f32 v40, v38, s0
	v_fmac_f32_e32 v7, v37, v5
	v_lshl_add_u64 v[38:39], v[20:21], 0, s[24:25]
	v_cvt_pk_bf16_f32 v5, v7, s0
	global_store_short v[38:39], v40, off
	global_store_short v[38:39], v5, off offset:64
	s_branch .LBB0_1141
